# v23: v21 + mLSTM role dispatch before barrier 1 as direct branches (flag maze removed)
# speedup vs baseline: 1.0087x; 1.0063x over previous
; #define LAS __attribute__((address_space(3)))
; DEV uint4 pack8(const float* f) { return make_uint4(pk2(f[0], f[1]), pk2(f[2], f[3]), pk2(f[4], f[5]), pk2(f[6], f[7])); }
; template <int SKIP>
; DEV void mlstm_phase(LAS char* shm, const bf16_t* q, const bf16_t* k, const bf16_t* v, const float* gpart, const float* b_ig, const float* b_fg, bf16_t* hc, const bool pre) {
;     ...
;             if (wid < 4) asm volatile("s_waitcnt vmcnt(1)" ::: "memory");
;             else asm volatile("s_waitcnt vmcnt(0)" ::: "memory");
;             if (wid < 4) {
;                 const int s_ = tid >> 2, v0 = (tid & 3) * 8;
;                 const float ws = __expf(ta[j * 64 + s_] - mxc);
;                 float f8[8]; unpack8(vv, f8);
; #pragma unroll
;                 for (int e = 0; e < 8; ++e) f8[e] *= ws;
;                 const uint4 wv = pack8(f8);
;                 *(LAS u32x4*)(shm + VT + s_ * VRS + v0 * 2) = (u32x4){vv.x, vv.y, vv.z, vv.w};
;                 *(LAS u32x4*)(shm + VWT + s_ * VRS + v0 * 2) = (u32x4){wv.x, wv.y, wv.z, wv.w};
;             } else if (wid == 4) {
;                 const int s_ = tid - 256;
;                 *(LAS u32x4*)(shm + VWT + s_ * VRS + 64) = (u32x4){(unsigned)f2bf(__expf(ta[j * 64 + s_] - mxc)), 0u, 0u, 0u};
;             }
.LBB0_636:
	s_add_i32 s0, s41, 4
	v_mov_b32_e32 v0, s0
	v_max_f32_e64 v227, s28, s28
	s_mov_b64 s[0:1], -1
	s_and_b64 vcc, exec, s[84:85]
	v_readfirstlane_b32 s29, v241
	v_readfirstlane_b32 s42, v239
	ds_read_b32 v239, v0
	ds_read_b32 v241, v0 offset:4
	v_max_f32_e64 v0, s29, s29
	v_max_f32_e32 v0, v227, v0
	s_nop 0
	v_readfirstlane_b32 s43, v0
	v_add_u32_e32 v0, s40, v200
	v_add_u32_e32 v0, 0x21500, v0
	ds_read_b32 v250, v0
	s_cbranch_vccnz .LBB0_643
	s_waitcnt vmcnt(1)
	s_branch .LBB0_648

; template <int SKIP>
; DEV void mlstm_phase(LAS char* shm, const bf16_t* q, const bf16_t* k, const bf16_t* v, const float* gpart, const float* b_ig, const float* b_fg, bf16_t* hc, const bool pre) {
;     ...
;             if (wid < 4) asm volatile("s_waitcnt vmcnt(1)" ::: "memory");
;             else asm volatile("s_waitcnt vmcnt(0)" ::: "memory");
.LBB0_643:
	s_waitcnt vmcnt(0)
	s_branch .LBB0_645

; #define LAS __attribute__((address_space(3)))
; DEV uint4 pack8(const float* f) { return make_uint4(pk2(f[0], f[1]), pk2(f[2], f[3]), pk2(f[4], f[5]), pk2(f[6], f[7])); }
; template <int SKIP>
; DEV void mlstm_phase(LAS char* shm, const bf16_t* q, const bf16_t* k, const bf16_t* v, const float* gpart, const float* b_ig, const float* b_fg, bf16_t* hc, const bool pre) {
;     ...
;             if (wid < 4) asm volatile("s_waitcnt vmcnt(1)" ::: "memory");
;             else asm volatile("s_waitcnt vmcnt(0)" ::: "memory");
;             if (wid < 4) {
;                 const int s_ = tid >> 2, v0 = (tid & 3) * 8;
;                 const float ws = __expf(ta[j * 64 + s_] - mxc);
;                 float f8[8]; unpack8(vv, f8);
; #pragma unroll
;                 for (int e = 0; e < 8; ++e) f8[e] *= ws;
;                 const uint4 wv = pack8(f8);
;                 *(LAS u32x4*)(shm + VT + s_ * VRS + v0 * 2) = (u32x4){vv.x, vv.y, vv.z, vv.w};
;                 *(LAS u32x4*)(shm + VWT + s_ * VRS + v0 * 2) = (u32x4){wv.x, wv.y, wv.z, wv.w};
;             } else if (wid == 4) {
;                 const int s_ = tid - 256;
;                 *(LAS u32x4*)(shm + VWT + s_ * VRS + 64) = (u32x4){(unsigned)f2bf(__expf(ta[j * 64 + s_] - mxc)), 0u, 0u, 0u};
;             }
.LBB0_1487:
	s_add_i32 s0, s41, 4
	v_mov_b32_e32 v0, s0
	v_max_f32_e64 v227, s28, s28
	s_mov_b64 s[0:1], -1
	s_and_b64 vcc, exec, s[70:71]
	v_readfirstlane_b32 s29, v253
	v_readfirstlane_b32 s42, v252
	ds_read_b32 v252, v0
	ds_read_b32 v253, v0 offset:4
	v_max_f32_e64 v0, s29, s29
	v_max_f32_e32 v0, v227, v0
	s_nop 0
	v_readfirstlane_b32 s43, v0
	v_add_u32_e32 v0, s40, v200
	v_add_u32_e32 v0, 0x21500, v0
	ds_read_b32 v248, v0
	s_cbranch_vccnz .LBB0_1494
	s_waitcnt vmcnt(1)
	s_branch .LBB0_1499
